# sample-attention key-norm MFMAs reordered: four independent accumulators first, then the four accumulate MFMAs; kb0 squares interleaved with kb1 first MFMAs
# speedup vs baseline: 1.0047x; 1.0005x over previous
; #define LAS __attribute__((address_space(3)))
; DI void attn_sample_phase(const Args& a, LAS unsigned char* lds, int vcu, int G, int tid, int lane, int wave) {
;     ...
;             { const LAS unsigned char* c8b = C8 + (j & 1) * 8704; const LAS float* spe = SSPE + (j & 1) * 32;
; #pragma unroll
;                 for (int kb = 0; kb < 2; ++kb) { f32x4 acc[4] = {};
; #pragma unroll
;                     for (int ks = 0; ks < 2; ++ks) { const LAS unsigned char* ap = c8b + (kb * 16 + r16) * 272 + 128 * ks + 32 * q4;
;                         const u32x4 x0 = *(const LAS u32x4*)ap, x1 = *(const LAS u32x4*)(ap + 16);
;                         const v8i_t af = {(int)x0.x, (int)x0.y, (int)x0.z, (int)x0.w, (int)x1.x, (int)x1.y, (int)x1.z, (int)x1.w};
; #pragma unroll
;                         for (int nb = 0; nb < 4; ++nb) acc[nb] = __builtin_amdgcn_mfma_scale_f32_16x16x128_f8f6f4(af, wf8[nb][ks], acc[nb], 0, 0, 0, 0x7F7F7F7F, 0, 0x7F7F7F7F); }
;                     f32x4 sq = (acc[0] * acc[0] + acc[1] * acc[1] + acc[2] * acc[2] + acc[3] * acc[3]) * (1.f / 256.f);
;                     sq.x = row16_sum(sq.x); sq.y = row16_sum(sq.y); sq.z = row16_sum(sq.z); sq.w = row16_sum(sq.w);
;                     if (r16 == 0) { const f32x4 pe = *(const LAS f32x4*)(spe + kb * 16 + 4 * q4); f32x4 r;
;                         r.x = __builtin_amdgcn_rsqf((sq.x + pe.x) * (1.f / 96.f) + EPS); r.y = __builtin_amdgcn_rsqf((sq.y + pe.y) * (1.f / 96.f) + EPS);
;                         r.z = __builtin_amdgcn_rsqf((sq.z + pe.z) * (1.f / 96.f) + EPS); r.w = __builtin_amdgcn_rsqf((sq.w + pe.w) * (1.f / 96.f) + EPS);
;                         *(LAS f32x4*)(RI + wave * 32 + kb * 16 + 4 * q4) = r; } } }
.LBB0_904:
	s_add_i32 s26, s25, -2
	s_and_b32 s8, s26, 1
	s_mul_i32 s9, s8, 0x2200
	v_add_u32_e32 v2, s9, v202
	s_lshl_b32 s8, s8, 7
	v_lshl_add_u32 v254, v140, 2, s8
	v_add_u32_e32 v254, 0x17a00, v254
	ds_read_b128 v[212:215], v2 offset:56832
	ds_read_b128 v[216:219], v2 offset:56848
	ds_read_b128 v[236:239], v2 offset:56960
	ds_read_b128 v[240:243], v2 offset:56976
	ds_read_b128 v[246:249], v2 offset:61184
	ds_read_b128 v[250:253], v2 offset:61200
	ds_read_b32 v232, v254
	ds_read_b32 v233, v254 offset:64
	s_waitcnt lgkmcnt(6)
	v_mfma_scale_f32_16x16x128_f8f6f4 v[220:223], v[36:43], v[212:219], 0, v208, v208 op_sel_hi:[0,0,0]
	v_mfma_scale_f32_16x16x128_f8f6f4 v[136:139], v[20:27], v[212:219], 0, v208, v208 op_sel_hi:[0,0,0]
	v_mfma_scale_f32_16x16x128_f8f6f4 v[224:227], v[52:59], v[212:219], 0, v208, v208 op_sel_hi:[0,0,0]
	v_mfma_scale_f32_16x16x128_f8f6f4 v[228:231], v[68:75], v[212:219], 0, v208, v208 op_sel_hi:[0,0,0]
	s_waitcnt lgkmcnt(4)
	v_mfma_scale_f32_16x16x128_f8f6f4 v[220:223], v[44:51], v[236:243], v[220:223], v208, v208 op_sel_hi:[0,0,0]
	ds_read_b128 v[212:215], v2 offset:61312
	ds_read_b128 v[216:219], v2 offset:61328
	v_mfma_scale_f32_16x16x128_f8f6f4 v[136:139], v[28:35], v[236:243], v[136:139], v208, v208 op_sel_hi:[0,0,0]
	v_mfma_scale_f32_16x16x128_f8f6f4 v[224:227], v[60:67], v[236:243], v[224:227], v208, v208 op_sel_hi:[0,0,0]
	v_mfma_scale_f32_16x16x128_f8f6f4 v[228:231], v[76:83], v[236:243], v[228:231], v208, v208 op_sel_hi:[0,0,0]
	v_lshlrev_b32_e32 v255, 7, v158
	v_lshl_add_u32 v255, v140, 2, v255
	v_add_u32_e32 v255, 0x17600, v255
	s_mov_b64 s[100:101], 0xffff
	s_nop 4
	v_mul_f32_e32 v234, v220, v220
	v_fmac_f32_e32 v234, v221, v221
	v_fmac_f32_e32 v234, v222, v222
	v_fmac_f32_e32 v234, v223, v223
	s_waitcnt lgkmcnt(4)
	v_mfma_scale_f32_16x16x128_f8f6f4 v[220:223], v[36:43], v[246:253], 0, v208, v208 op_sel_hi:[0,0,0]
	v_fmac_f32_e32 v234, v136, v136
	v_fmac_f32_e32 v234, v137, v137
	v_fmac_f32_e32 v234, v138, v138
	v_fmac_f32_e32 v234, v139, v139
	v_mfma_scale_f32_16x16x128_f8f6f4 v[136:139], v[68:75], v[246:253], 0, v208, v208 op_sel_hi:[0,0,0]
	v_fmac_f32_e32 v234, v224, v224
	v_fmac_f32_e32 v234, v225, v225
	v_fmac_f32_e32 v234, v226, v226
	v_fmac_f32_e32 v234, v227, v227
	v_mfma_scale_f32_16x16x128_f8f6f4 v[224:227], v[20:27], v[246:253], 0, v208, v208 op_sel_hi:[0,0,0]
	v_fmac_f32_e32 v234, v228, v228
	v_fmac_f32_e32 v234, v229, v229
	v_fmac_f32_e32 v234, v230, v230
	v_fmac_f32_e32 v234, v231, v231
	v_mfma_scale_f32_16x16x128_f8f6f4 v[228:231], v[52:59], v[246:253], 0, v208, v208 op_sel_hi:[0,0,0]
	s_waitcnt lgkmcnt(0)
	v_mov_b32_e32 v235, v234
	v_mfma_scale_f32_16x16x128_f8f6f4 v[220:223], v[44:51], v[212:219], v[220:223], v208, v208 op_sel_hi:[0,0,0]
	s_nop 0
	v_permlane32_swap_b32_e32 v235, v234
	v_add_f32_e32 v234, v234, v235
	v_mfma_scale_f32_16x16x128_f8f6f4 v[136:139], v[76:83], v[212:219], v[136:139], v208, v208 op_sel_hi:[0,0,0]
	v_mov_b32_e32 v235, v234
	s_nop 1
	v_permlane16_swap_b32_e32 v235, v234
	v_add_f32_e32 v234, v234, v235
	v_mfma_scale_f32_16x16x128_f8f6f4 v[224:227], v[28:35], v[212:219], v[224:227], v208, v208 op_sel_hi:[0,0,0]
	v_fmamk_f32 v234, v234, 0x3b800000, v232
	v_fmamk_f32 v234, v234, 0x3c2aaaab, v209
	v_rsq_f32_e32 v234, v234
	v_mfma_scale_f32_16x16x128_f8f6f4 v[228:231], v[60:67], v[212:219], v[228:231], v208, v208 op_sel_hi:[0,0,0]
	s_and_saveexec_b64 s[18:19], s[100:101]
	ds_write_b32 v255, v234
	s_or_b64 exec, exec, s[18:19]
	v_mul_f32_e32 v234, v220, v220
	v_fmac_f32_e32 v234, v221, v221
	v_fmac_f32_e32 v234, v222, v222
	v_fmac_f32_e32 v234, v223, v223
	v_fmac_f32_e32 v234, v136, v136
	v_fmac_f32_e32 v234, v137, v137
	v_fmac_f32_e32 v234, v138, v138
	v_fmac_f32_e32 v234, v139, v139
	v_fmac_f32_e32 v234, v224, v224
	v_fmac_f32_e32 v234, v225, v225
	v_fmac_f32_e32 v234, v226, v226
	v_fmac_f32_e32 v234, v227, v227
	v_fmac_f32_e32 v234, v228, v228
	v_fmac_f32_e32 v234, v229, v229
	v_fmac_f32_e32 v234, v230, v230
	v_fmac_f32_e32 v234, v231, v231
	v_mov_b32_e32 v235, v234
	s_nop 1
	v_permlane32_swap_b32_e32 v235, v234
	v_add_f32_e32 v234, v234, v235
	v_mov_b32_e32 v235, v234
	s_nop 1
	v_permlane16_swap_b32_e32 v235, v234
	v_add_f32_e32 v234, v234, v235
	v_fmamk_f32 v234, v234, 0x3b800000, v233
	v_fmamk_f32 v234, v234, 0x3c2aaaab, v209
	v_rsq_f32_e32 v234, v234
	s_and_saveexec_b64 s[18:19], s[100:101]
	ds_write_b32 v255, v234 offset:64
	s_or_b64 exec, exec, s[18:19]
